# SwiGLU epilogue: 64 serial silu chains re-emitted 8 at a time stage-by-stage on dedicated temps (no hazard nops, ILP)
# speedup vs baseline: 1.0037x; 1.0033x over previous
.LBB0_217:
	ds_read_b128 v[144:147], v220 offset:0
	ds_read_b128 v[148:151], v220 offset:1024
	ds_read_b128 v[152:155], v220 offset:2048
	ds_read_b128 v[156:159], v220 offset:3072
	ds_read_b128 v[160:163], v143
	ds_read_b128 v[164:167], v143 offset:1024
	ds_read_b128 v[168:171], v143 offset:2048
	ds_read_b128 v[172:175], v143 offset:3072
	ds_read_b128 v[176:179], v143 offset:4096
	ds_read_b128 v[180:183], v143 offset:5120
	ds_read_b128 v[184:187], v143 offset:6144
	ds_read_b128 v[188:191], v143 offset:7168
	global_load_lds_dwordx4 v134, s[14:15]
	s_add_i32 m0, s13, 0xe000
	s_nop 0
	global_load_lds_dwordx4 v136, s[14:15]
	s_waitcnt lgkmcnt(8)
	s_barrier
	s_waitcnt lgkmcnt(0)
	v_mfma_f32_16x16x32_bf16 v[124:127], v[144:147], v[160:163], v[124:127]
	v_mfma_f32_16x16x32_bf16 v[116:119], v[152:155], v[160:163], v[116:119]
	v_mfma_f32_16x16x32_bf16 v[108:111], v[144:147], v[168:171], v[108:111]
	v_mfma_f32_16x16x32_bf16 v[100:103], v[152:155], v[168:171], v[100:103]
	s_add_i32 s44, 0, 0x14000
	s_add_i32 s41, s41, s26
	v_mfma_f32_16x16x32_bf16 v[92:95], v[144:147], v[176:179], v[92:95]
	s_mov_b32 m0, s41
	v_mfma_f32_16x16x32_bf16 v[84:87], v[152:155], v[176:179], v[84:87]
	v_mfma_f32_16x16x32_bf16 v[76:79], v[144:147], v[184:187], v[76:79]
	v_mfma_f32_16x16x32_bf16 v[68:71], v[152:155], v[184:187], v[68:71]
	v_mfma_f32_16x16x32_bf16 v[124:127], v[148:151], v[164:167], v[124:127]
	v_mfma_f32_16x16x32_bf16 v[116:119], v[156:159], v[164:167], v[116:119]
	v_mfma_f32_16x16x32_bf16 v[108:111], v[148:151], v[172:175], v[108:111]
	v_mfma_f32_16x16x32_bf16 v[100:103], v[156:159], v[172:175], v[100:103]
	v_mfma_f32_16x16x32_bf16 v[92:95], v[148:151], v[180:183], v[92:95]
	v_mfma_f32_16x16x32_bf16 v[84:87], v[156:159], v[180:183], v[84:87]
	v_mfma_f32_16x16x32_bf16 v[76:79], v[148:151], v[188:191], v[76:79]
	v_mfma_f32_16x16x32_bf16 v[68:71], v[156:159], v[188:191], v[68:71]
	s_barrier
	ds_read_b128 v[196:199], v220 offset:16384
	ds_read_b128 v[204:207], v220 offset:17408
	ds_read_b128 v[208:211], v220 offset:18432
	ds_read_b128 v[214:217], v220 offset:19456
	global_load_lds_dwordx4 v192, s[16:17]
	s_add_i32 m0, s41, 0x2000
	s_nop 0
	global_load_lds_dwordx4 v128, s[16:17]
	s_barrier
	s_waitcnt lgkmcnt(0)
	v_mfma_f32_16x16x32_bf16 v[120:123], v[196:199], v[160:163], v[120:123]
	v_mfma_f32_16x16x32_bf16 v[112:115], v[208:211], v[160:163], v[112:115]
	v_mfma_f32_16x16x32_bf16 v[104:107], v[196:199], v[168:171], v[104:107]
	v_mfma_f32_16x16x32_bf16 v[96:99], v[208:211], v[168:171], v[96:99]
	s_mov_b32 m0, s13
	v_mfma_f32_16x16x32_bf16 v[88:91], v[196:199], v[176:179], v[88:91]
	s_add_u32 s48, s18, 0x80
	s_addc_u32 s49, s19, 0
	v_mfma_f32_16x16x32_bf16 v[80:83], v[208:211], v[176:179], v[80:83]
	v_mfma_f32_16x16x32_bf16 v[72:75], v[196:199], v[184:187], v[72:75]
	v_mfma_f32_16x16x32_bf16 v[64:67], v[208:211], v[184:187], v[64:67]
	v_mfma_f32_16x16x32_bf16 v[120:123], v[204:207], v[164:167], v[120:123]
	v_mfma_f32_16x16x32_bf16 v[112:115], v[214:217], v[164:167], v[112:115]
	v_mfma_f32_16x16x32_bf16 v[104:107], v[204:207], v[172:175], v[104:107]
	v_mfma_f32_16x16x32_bf16 v[96:99], v[214:217], v[172:175], v[96:99]
	v_mfma_f32_16x16x32_bf16 v[88:91], v[204:207], v[180:183], v[88:91]
	v_mfma_f32_16x16x32_bf16 v[80:83], v[214:217], v[180:183], v[80:83]
	v_mfma_f32_16x16x32_bf16 v[72:75], v[204:207], v[188:191], v[72:75]
	v_mfma_f32_16x16x32_bf16 v[64:67], v[214:217], v[188:191], v[64:67]
	s_barrier
	ds_read_b128 v[160:163], v143 offset:16384
	ds_read_b128 v[164:167], v143 offset:17408
	ds_read_b128 v[168:171], v143 offset:18432
	ds_read_b128 v[172:175], v143 offset:19456
	ds_read_b128 v[176:179], v143 offset:20480
	ds_read_b128 v[180:183], v143 offset:21504
	ds_read_b128 v[184:187], v143 offset:22528
	ds_read_b128 v[188:191], v143 offset:23552
	global_load_lds_dwordx4 v132, s[18:19]
	s_mov_b32 m0, s28
	s_nop 0
	global_load_lds_dwordx4 v130, s[18:19]
	s_barrier
	s_waitcnt lgkmcnt(0)
	v_mfma_f32_16x16x32_bf16 v[60:63], v[144:147], v[160:163], v[60:63]
	v_mfma_f32_16x16x32_bf16 v[52:55], v[152:155], v[160:163], v[52:55]
	v_mfma_f32_16x16x32_bf16 v[44:47], v[144:147], v[168:171], v[44:47]
	v_mfma_f32_16x16x32_bf16 v[36:39], v[152:155], v[168:171], v[36:39]
	s_add_u32 s42, s16, 0x80000
	s_addc_u32 s43, s17, 0
	v_mfma_f32_16x16x32_bf16 v[28:31], v[144:147], v[176:179], v[28:31]
	s_add_i32 s41, s44, s26
	s_mov_b32 m0, s41
	v_mfma_f32_16x16x32_bf16 v[20:23], v[152:155], v[176:179], v[20:23]
	v_mfma_f32_16x16x32_bf16 v[12:15], v[144:147], v[184:187], v[12:15]
	v_mfma_f32_16x16x32_bf16 v[4:7], v[152:155], v[184:187], v[4:7]
	v_mfma_f32_16x16x32_bf16 v[60:63], v[148:151], v[164:167], v[60:63]
	v_mfma_f32_16x16x32_bf16 v[52:55], v[156:159], v[164:167], v[52:55]
	v_mfma_f32_16x16x32_bf16 v[44:47], v[148:151], v[172:175], v[44:47]
	v_mfma_f32_16x16x32_bf16 v[36:39], v[156:159], v[172:175], v[36:39]
	v_mfma_f32_16x16x32_bf16 v[28:31], v[148:151], v[180:183], v[28:31]
	v_mfma_f32_16x16x32_bf16 v[20:23], v[156:159], v[180:183], v[20:23]
	v_mfma_f32_16x16x32_bf16 v[12:15], v[148:151], v[188:191], v[12:15]
	v_mfma_f32_16x16x32_bf16 v[4:7], v[156:159], v[188:191], v[4:7]
	s_barrier
	global_load_lds_dwordx4 v192, s[42:43]
	s_add_i32 m0, s41, 0x2000
	s_nop 0
	global_load_lds_dwordx4 v128, s[42:43]
	s_waitcnt vmcnt(6)
	s_barrier
	v_mfma_f32_16x16x32_bf16 v[56:59], v[196:199], v[160:163], v[56:59]
	v_mfma_f32_16x16x32_bf16 v[48:51], v[208:211], v[160:163], v[48:51]
	v_mfma_f32_16x16x32_bf16 v[40:43], v[196:199], v[168:171], v[40:43]
	v_mfma_f32_16x16x32_bf16 v[32:35], v[208:211], v[168:171], v[32:35]
	s_add_i32 s41, 0, 0x18000
	v_mfma_f32_16x16x32_bf16 v[24:27], v[196:199], v[176:179], v[24:27]
	s_add_u32 s18, s18, 0x80000
	s_addc_u32 s19, s19, 0
	v_mfma_f32_16x16x32_bf16 v[16:19], v[208:211], v[176:179], v[16:19]
	s_mov_b32 m0, s29
	v_mfma_f32_16x16x32_bf16 v[8:11], v[196:199], v[184:187], v[8:11]
	v_mfma_f32_16x16x32_bf16 v[0:3], v[208:211], v[184:187], v[0:3]
	v_mfma_f32_16x16x32_bf16 v[56:59], v[204:207], v[164:167], v[56:59]
	v_mfma_f32_16x16x32_bf16 v[48:51], v[214:217], v[164:167], v[48:51]
	v_mfma_f32_16x16x32_bf16 v[40:43], v[204:207], v[172:175], v[40:43]
	v_mfma_f32_16x16x32_bf16 v[32:35], v[214:217], v[172:175], v[32:35]
	v_mfma_f32_16x16x32_bf16 v[24:27], v[204:207], v[180:183], v[24:27]
	v_mfma_f32_16x16x32_bf16 v[16:19], v[214:217], v[180:183], v[16:19]
	v_mfma_f32_16x16x32_bf16 v[8:11], v[204:207], v[188:191], v[8:11]
	v_mfma_f32_16x16x32_bf16 v[0:3], v[214:217], v[188:191], v[0:3]
	s_barrier
	ds_read_b128 v[144:147], v220 offset:32768
	ds_read_b128 v[148:151], v220 offset:33792
	ds_read_b128 v[152:155], v220 offset:34816
	ds_read_b128 v[156:159], v220 offset:35840
	ds_read_b128 v[160:163], v143 offset:32768
	ds_read_b128 v[164:167], v143 offset:33792
	ds_read_b128 v[168:171], v143 offset:34816
	ds_read_b128 v[172:175], v143 offset:35840
	ds_read_b128 v[176:179], v143 offset:36864
	ds_read_b128 v[180:183], v143 offset:37888
	ds_read_b128 v[184:187], v143 offset:38912
	ds_read_b128 v[188:191], v143 offset:39936
	global_load_lds_dwordx4 v132, s[18:19]
	s_mov_b32 m0, s30
	s_nop 0
	global_load_lds_dwordx4 v130, s[18:19]
	s_waitcnt lgkmcnt(8)
	s_barrier
	s_waitcnt lgkmcnt(0)
	v_mfma_f32_16x16x32_bf16 v[124:127], v[144:147], v[160:163], v[124:127]
	v_mfma_f32_16x16x32_bf16 v[116:119], v[152:155], v[160:163], v[116:119]
	v_mfma_f32_16x16x32_bf16 v[108:111], v[144:147], v[168:171], v[108:111]
	v_mfma_f32_16x16x32_bf16 v[100:103], v[152:155], v[168:171], v[100:103]
	s_add_i32 s18, 0, 0x1c000
	s_add_i32 s19, s41, s26
	v_mfma_f32_16x16x32_bf16 v[92:95], v[144:147], v[176:179], v[92:95]
	s_add_i32 m0, s19, 0xffffff80
	v_mfma_f32_16x16x32_bf16 v[84:87], v[152:155], v[176:179], v[84:87]
	v_mfma_f32_16x16x32_bf16 v[76:79], v[144:147], v[184:187], v[76:79]
	v_mfma_f32_16x16x32_bf16 v[68:71], v[152:155], v[184:187], v[68:71]
	v_mfma_f32_16x16x32_bf16 v[124:127], v[148:151], v[164:167], v[124:127]
	v_mfma_f32_16x16x32_bf16 v[116:119], v[156:159], v[164:167], v[116:119]
	v_mfma_f32_16x16x32_bf16 v[108:111], v[148:151], v[172:175], v[108:111]
	v_mfma_f32_16x16x32_bf16 v[100:103], v[156:159], v[172:175], v[100:103]
	v_mfma_f32_16x16x32_bf16 v[92:95], v[148:151], v[180:183], v[92:95]
	v_mfma_f32_16x16x32_bf16 v[84:87], v[156:159], v[180:183], v[84:87]
	v_mfma_f32_16x16x32_bf16 v[76:79], v[148:151], v[188:191], v[76:79]
	v_mfma_f32_16x16x32_bf16 v[68:71], v[156:159], v[188:191], v[68:71]
	s_barrier
	ds_read_b128 v[196:199], v220 offset:49152
	ds_read_b128 v[204:207], v220 offset:50176
	ds_read_b128 v[208:211], v220 offset:51200
	ds_read_b128 v[214:217], v220 offset:52224
	global_load_lds_dwordx4 v192, s[16:17] offset:128
	s_add_i32 m0, s19, 0x1f80
	s_nop 0
	global_load_lds_dwordx4 v128, s[16:17] offset:128
	s_barrier
	s_waitcnt lgkmcnt(0)
	v_mfma_f32_16x16x32_bf16 v[120:123], v[196:199], v[160:163], v[120:123]
	v_mfma_f32_16x16x32_bf16 v[112:115], v[208:211], v[160:163], v[112:115]
	v_mfma_f32_16x16x32_bf16 v[104:107], v[196:199], v[168:171], v[104:107]
	v_mfma_f32_16x16x32_bf16 v[96:99], v[208:211], v[168:171], v[96:99]
	s_mov_b32 m0, s33
	v_mfma_f32_16x16x32_bf16 v[88:91], v[196:199], v[176:179], v[88:91]
	v_mfma_f32_16x16x32_bf16 v[80:83], v[208:211], v[176:179], v[80:83]
	v_mfma_f32_16x16x32_bf16 v[72:75], v[196:199], v[184:187], v[72:75]
	v_mfma_f32_16x16x32_bf16 v[64:67], v[208:211], v[184:187], v[64:67]
	v_mfma_f32_16x16x32_bf16 v[120:123], v[204:207], v[164:167], v[120:123]
	v_mfma_f32_16x16x32_bf16 v[112:115], v[214:217], v[164:167], v[112:115]
	v_mfma_f32_16x16x32_bf16 v[104:107], v[204:207], v[172:175], v[104:107]
	v_mfma_f32_16x16x32_bf16 v[96:99], v[214:217], v[172:175], v[96:99]
	v_mfma_f32_16x16x32_bf16 v[88:91], v[204:207], v[180:183], v[88:91]
	v_mfma_f32_16x16x32_bf16 v[80:83], v[214:217], v[180:183], v[80:83]
	v_mfma_f32_16x16x32_bf16 v[72:75], v[204:207], v[188:191], v[72:75]
	v_mfma_f32_16x16x32_bf16 v[64:67], v[214:217], v[188:191], v[64:67]
	s_barrier
	ds_read_b128 v[160:163], v143 offset:49152
	ds_read_b128 v[164:167], v143 offset:50176
	ds_read_b128 v[168:171], v143 offset:51200
	ds_read_b128 v[172:175], v143 offset:52224
	ds_read_b128 v[176:179], v143 offset:53248
	ds_read_b128 v[180:183], v143 offset:54272
	ds_read_b128 v[184:187], v143 offset:55296
	ds_read_b128 v[188:191], v143 offset:56320
	global_load_lds_dwordx4 v132, s[48:49]
	s_mov_b32 m0, s34
	s_nop 0
	global_load_lds_dwordx4 v130, s[48:49]
	s_barrier
	s_waitcnt lgkmcnt(0)
	v_mfma_f32_16x16x32_bf16 v[60:63], v[144:147], v[160:163], v[60:63]
	v_mfma_f32_16x16x32_bf16 v[52:55], v[152:155], v[160:163], v[52:55]
	v_mfma_f32_16x16x32_bf16 v[44:47], v[144:147], v[168:171], v[44:47]
	v_mfma_f32_16x16x32_bf16 v[36:39], v[152:155], v[168:171], v[36:39]
	s_add_u32 s16, s16, 0x80080
	s_addc_u32 s17, s17, 0
	v_mfma_f32_16x16x32_bf16 v[28:31], v[144:147], v[176:179], v[28:31]
	s_add_i32 s18, s18, s26
	s_mov_b32 m0, s18
	v_mfma_f32_16x16x32_bf16 v[20:23], v[152:155], v[176:179], v[20:23]
	v_mfma_f32_16x16x32_bf16 v[12:15], v[144:147], v[184:187], v[12:15]
	v_mfma_f32_16x16x32_bf16 v[4:7], v[152:155], v[184:187], v[4:7]
	v_mfma_f32_16x16x32_bf16 v[60:63], v[148:151], v[164:167], v[60:63]
	v_mfma_f32_16x16x32_bf16 v[52:55], v[156:159], v[164:167], v[52:55]
	v_mfma_f32_16x16x32_bf16 v[44:47], v[148:151], v[172:175], v[44:47]
	v_mfma_f32_16x16x32_bf16 v[36:39], v[156:159], v[172:175], v[36:39]
	v_mfma_f32_16x16x32_bf16 v[28:31], v[148:151], v[180:183], v[28:31]
	v_mfma_f32_16x16x32_bf16 v[20:23], v[156:159], v[180:183], v[20:23]
	v_mfma_f32_16x16x32_bf16 v[12:15], v[148:151], v[188:191], v[12:15]
	v_mfma_f32_16x16x32_bf16 v[4:7], v[156:159], v[188:191], v[4:7]
	s_barrier
	global_load_lds_dwordx4 v192, s[16:17]
	s_add_i32 m0, s18, 0x2000
	s_nop 0
	global_load_lds_dwordx4 v128, s[16:17]
	s_waitcnt vmcnt(6)
	s_barrier
	v_mfma_f32_16x16x32_bf16 v[56:59], v[196:199], v[160:163], v[56:59]
	v_mfma_f32_16x16x32_bf16 v[48:51], v[208:211], v[160:163], v[48:51]
	v_mfma_f32_16x16x32_bf16 v[40:43], v[196:199], v[168:171], v[40:43]
	v_mfma_f32_16x16x32_bf16 v[32:35], v[208:211], v[168:171], v[32:35]
	s_add_i32 s40, s40, 2
	v_mfma_f32_16x16x32_bf16 v[24:27], v[196:199], v[176:179], v[24:27]
	s_add_u32 s14, s14, 0x100
	s_addc_u32 s15, s15, 0
	v_mfma_f32_16x16x32_bf16 v[16:19], v[208:211], v[176:179], v[16:19]
	s_add_u32 s38, s38, 0x100
	s_addc_u32 s39, s39, 0
	v_mfma_f32_16x16x32_bf16 v[8:11], v[196:199], v[184:187], v[8:11]
	s_add_u32 s16, s14, 0xfff80080
	s_addc_u32 s17, s15, -1
	v_mfma_f32_16x16x32_bf16 v[0:3], v[208:211], v[184:187], v[0:3]
	s_add_i32 s41, 0, 0x10000
	s_cmp_eq_u32 s40, 28
	v_mfma_f32_16x16x32_bf16 v[56:59], v[204:207], v[164:167], v[56:59]
	s_cselect_b32 s19, s7, s17
	s_cselect_b32 s18, s36, s16
	v_mfma_f32_16x16x32_bf16 v[48:51], v[214:217], v[164:167], v[48:51]
	s_cselect_b32 s17, s5, s39
	s_cselect_b32 s16, s37, s38
	v_mfma_f32_16x16x32_bf16 v[40:43], v[204:207], v[172:175], v[40:43]
	s_add_i32 m0, s13, 0xc000
	v_mfma_f32_16x16x32_bf16 v[32:35], v[214:217], v[172:175], v[32:35]
	v_mfma_f32_16x16x32_bf16 v[24:27], v[204:207], v[180:183], v[24:27]
	v_mfma_f32_16x16x32_bf16 v[16:19], v[214:217], v[180:183], v[16:19]
	v_mfma_f32_16x16x32_bf16 v[8:11], v[204:207], v[188:191], v[8:11]
	v_mfma_f32_16x16x32_bf16 v[0:3], v[214:217], v[188:191], v[0:3]
	s_cmp_gt_u32 s40, 29
	s_barrier
	s_cbranch_scc0 .LBB0_217
	v_mul_f32_e32 v222, 0xbfb8aa3b, v124
	v_mul_f32_e32 v223, 0xbfb8aa3b, v125
	v_mul_f32_e32 v224, 0xbfb8aa3b, v126
	v_mul_f32_e32 v225, 0xbfb8aa3b, v127
	v_mul_f32_e32 v226, 0xbfb8aa3b, v116
	v_mul_f32_e32 v227, 0xbfb8aa3b, v117
	v_mul_f32_e32 v228, 0xbfb8aa3b, v118
	v_mul_f32_e32 v229, 0xbfb8aa3b, v119
	v_exp_f32_e32 v222, v222
	v_exp_f32_e32 v223, v223
	v_exp_f32_e32 v224, v224
	v_exp_f32_e32 v225, v225
	v_exp_f32_e32 v226, v226
	v_exp_f32_e32 v227, v227
	v_exp_f32_e32 v228, v228
	v_exp_f32_e32 v229, v229
	v_add_f32_e32 v222, 1.0, v222
	v_add_f32_e32 v223, 1.0, v223
	v_add_f32_e32 v224, 1.0, v224
	v_add_f32_e32 v225, 1.0, v225
	v_add_f32_e32 v226, 1.0, v226
	v_add_f32_e32 v227, 1.0, v227
	v_add_f32_e32 v228, 1.0, v228
	v_add_f32_e32 v229, 1.0, v229
	v_rcp_f32_e32 v222, v222
	v_rcp_f32_e32 v223, v223
	v_rcp_f32_e32 v224, v224
	v_rcp_f32_e32 v225, v225
	v_rcp_f32_e32 v226, v226
	v_rcp_f32_e32 v227, v227
	v_rcp_f32_e32 v228, v228
	v_rcp_f32_e32 v229, v229
	v_mul_f32_e32 v222, v124, v222
	v_mul_f32_e32 v223, v125, v223
	v_mul_f32_e32 v224, v126, v224
	v_mul_f32_e32 v225, v127, v225
	v_mul_f32_e32 v226, v116, v226
	v_mul_f32_e32 v227, v117, v227
	v_mul_f32_e32 v228, v118, v228
	v_mul_f32_e32 v229, v119, v229
	v_mul_f32_e32 v120, v222, v120
	v_mul_f32_e32 v121, v223, v121
	v_mul_f32_e32 v122, v224, v122
	v_mul_f32_e32 v123, v225, v123
	v_mul_f32_e32 v116, v226, v112
	v_mul_f32_e32 v117, v227, v113
	v_mul_f32_e32 v124, v228, v114
	v_mul_f32_e32 v125, v229, v115
	v_lshl_or_b32 v146, s35, 7, v142
	v_lshl_add_u32 v144, s12, 8, v140
	v_ashrrev_i32_e32 v147, 31, v146
	v_mov_b64_e32 v[138:139], s[2:3]
	s_movk_i32 s5, 0x2c00
	v_mad_i64_i32 v[148:149], s[14:15], v144, s5, v[138:139]
	s_and_b64 vcc, exec, s[0:1]
	s_mov_b32 s35, s4
	s_mov_b32 s12, s6
	s_mov_b64 s[16:17], s[10:11]
	v_cvt_pk_bf16_f32 v114, v120, v121
	v_lshlrev_b64 v[112:113], 1, v[146:147]
	v_lshl_add_u64 v[118:119], v[148:149], 0, v[112:113]
	v_cvt_pk_bf16_f32 v115, v122, v123
	v_cvt_pk_bf16_f32 v116, v116, v117
	v_cvt_pk_bf16_f32 v117, v124, v125
	global_store_dwordx4 v[118:119], v[114:117], off
	s_nop 1
	v_mul_f32_e32 v222, 0xbfb8aa3b, v108
	v_mul_f32_e32 v223, 0xbfb8aa3b, v109
	v_mul_f32_e32 v224, 0xbfb8aa3b, v110
	v_mul_f32_e32 v225, 0xbfb8aa3b, v111
	v_mul_f32_e32 v226, 0xbfb8aa3b, v100
	v_mul_f32_e32 v227, 0xbfb8aa3b, v101
	v_mul_f32_e32 v228, 0xbfb8aa3b, v102
	v_mul_f32_e32 v229, 0xbfb8aa3b, v103
	v_exp_f32_e32 v222, v222
	v_exp_f32_e32 v223, v223
	v_exp_f32_e32 v224, v224
	v_exp_f32_e32 v225, v225
	v_exp_f32_e32 v226, v226
	v_exp_f32_e32 v227, v227
	v_exp_f32_e32 v228, v228
	v_exp_f32_e32 v229, v229
	v_add_f32_e32 v222, 1.0, v222
	v_add_f32_e32 v223, 1.0, v223
	v_add_f32_e32 v224, 1.0, v224
	v_add_f32_e32 v225, 1.0, v225
	v_add_f32_e32 v226, 1.0, v226
	v_add_f32_e32 v227, 1.0, v227
	v_add_f32_e32 v228, 1.0, v228
	v_add_f32_e32 v229, 1.0, v229
	v_rcp_f32_e32 v222, v222
	v_rcp_f32_e32 v223, v223
	v_rcp_f32_e32 v224, v224
	v_rcp_f32_e32 v225, v225
	v_rcp_f32_e32 v226, v226
	v_rcp_f32_e32 v227, v227
	v_rcp_f32_e32 v228, v228
	v_rcp_f32_e32 v229, v229
	v_mul_f32_e32 v222, v108, v222
	v_mul_f32_e32 v223, v109, v223
	v_mul_f32_e32 v224, v110, v224
	v_mul_f32_e32 v225, v111, v225
	v_mul_f32_e32 v226, v100, v226
	v_mul_f32_e32 v227, v101, v227
	v_mul_f32_e32 v228, v102, v228
	v_mul_f32_e32 v229, v103, v229
	v_mul_f32_e32 v104, v222, v104
	v_mul_f32_e32 v105, v223, v105
	v_mul_f32_e32 v106, v224, v106
	v_mul_f32_e32 v107, v225, v107
	v_mul_f32_e32 v108, v226, v96
	v_mul_f32_e32 v109, v227, v97
	v_mul_f32_e32 v102, v228, v98
	v_mul_f32_e32 v99, v229, v99
	v_or_b32_e32 v114, 16, v144
	v_mad_i64_i32 v[114:115], s[14:15], v114, s5, v[138:139]
	v_lshl_add_u64 v[100:101], v[114:115], 0, v[112:113]
	v_cvt_pk_bf16_f32 v96, v104, v105
	v_cvt_pk_bf16_f32 v97, v106, v107
	v_cvt_pk_bf16_f32 v98, v108, v109
	v_cvt_pk_bf16_f32 v99, v102, v99
	global_store_dwordx4 v[100:101], v[96:99], off
	s_nop 1
	v_mul_f32_e32 v222, 0xbfb8aa3b, v92
	v_mul_f32_e32 v223, 0xbfb8aa3b, v93
	v_mul_f32_e32 v224, 0xbfb8aa3b, v94
	v_mul_f32_e32 v225, 0xbfb8aa3b, v95
	v_mul_f32_e32 v226, 0xbfb8aa3b, v84
	v_mul_f32_e32 v227, 0xbfb8aa3b, v85
	v_mul_f32_e32 v228, 0xbfb8aa3b, v86
	v_mul_f32_e32 v229, 0xbfb8aa3b, v87
	v_exp_f32_e32 v222, v222
	v_exp_f32_e32 v223, v223
	v_exp_f32_e32 v224, v224
	v_exp_f32_e32 v225, v225
	v_exp_f32_e32 v226, v226
	v_exp_f32_e32 v227, v227
	v_exp_f32_e32 v228, v228
	v_exp_f32_e32 v229, v229
	v_add_f32_e32 v222, 1.0, v222
	v_add_f32_e32 v223, 1.0, v223
	v_add_f32_e32 v224, 1.0, v224
	v_add_f32_e32 v225, 1.0, v225
	v_add_f32_e32 v226, 1.0, v226
	v_add_f32_e32 v227, 1.0, v227
	v_add_f32_e32 v228, 1.0, v228
	v_add_f32_e32 v229, 1.0, v229
	v_rcp_f32_e32 v222, v222
	v_rcp_f32_e32 v223, v223
	v_rcp_f32_e32 v224, v224
	v_rcp_f32_e32 v225, v225
	v_rcp_f32_e32 v226, v226
	v_rcp_f32_e32 v227, v227
	v_rcp_f32_e32 v228, v228
	v_rcp_f32_e32 v229, v229
	v_mul_f32_e32 v222, v92, v222
	v_mul_f32_e32 v223, v93, v223
	v_mul_f32_e32 v224, v94, v224
	v_mul_f32_e32 v225, v95, v225
	v_mul_f32_e32 v226, v84, v226
	v_mul_f32_e32 v227, v85, v227
	v_mul_f32_e32 v228, v86, v228
	v_mul_f32_e32 v229, v87, v229
	v_mul_f32_e32 v88, v222, v88
	v_mul_f32_e32 v89, v223, v89
	v_mul_f32_e32 v90, v224, v90
	v_mul_f32_e32 v91, v225, v91
	v_mul_f32_e32 v92, v226, v80
	v_mul_f32_e32 v93, v227, v81
	v_mul_f32_e32 v86, v228, v82
	v_mul_f32_e32 v83, v229, v83
	v_or_b32_e32 v96, 32, v144
	v_mad_i64_i32 v[96:97], s[14:15], v96, s5, v[138:139]
	v_lshl_add_u64 v[84:85], v[96:97], 0, v[112:113]
	v_cvt_pk_bf16_f32 v80, v88, v89
	v_cvt_pk_bf16_f32 v81, v90, v91
	v_cvt_pk_bf16_f32 v82, v92, v93
	v_cvt_pk_bf16_f32 v83, v86, v83
	global_store_dwordx4 v[84:85], v[80:83], off
	s_nop 1
	v_mul_f32_e32 v222, 0xbfb8aa3b, v76
	v_mul_f32_e32 v223, 0xbfb8aa3b, v77
	v_mul_f32_e32 v224, 0xbfb8aa3b, v78
	v_mul_f32_e32 v225, 0xbfb8aa3b, v79
	v_mul_f32_e32 v226, 0xbfb8aa3b, v68
	v_mul_f32_e32 v227, 0xbfb8aa3b, v69
	v_mul_f32_e32 v228, 0xbfb8aa3b, v70
	v_mul_f32_e32 v229, 0xbfb8aa3b, v71
	v_exp_f32_e32 v222, v222
	v_exp_f32_e32 v223, v223
	v_exp_f32_e32 v224, v224
	v_exp_f32_e32 v225, v225
	v_exp_f32_e32 v226, v226
	v_exp_f32_e32 v227, v227
	v_exp_f32_e32 v228, v228
	v_exp_f32_e32 v229, v229
	v_add_f32_e32 v222, 1.0, v222
	v_add_f32_e32 v223, 1.0, v223
	v_add_f32_e32 v224, 1.0, v224
	v_add_f32_e32 v225, 1.0, v225
	v_add_f32_e32 v226, 1.0, v226
	v_add_f32_e32 v227, 1.0, v227
	v_add_f32_e32 v228, 1.0, v228
	v_add_f32_e32 v229, 1.0, v229
	v_rcp_f32_e32 v222, v222
	v_rcp_f32_e32 v223, v223
	v_rcp_f32_e32 v224, v224
	v_rcp_f32_e32 v225, v225
	v_rcp_f32_e32 v226, v226
	v_rcp_f32_e32 v227, v227
	v_rcp_f32_e32 v228, v228
	v_rcp_f32_e32 v229, v229
	v_mul_f32_e32 v222, v76, v222
	v_mul_f32_e32 v223, v77, v223
	v_mul_f32_e32 v224, v78, v224
	v_mul_f32_e32 v225, v79, v225
	v_mul_f32_e32 v226, v68, v226
	v_mul_f32_e32 v227, v69, v227
	v_mul_f32_e32 v228, v70, v228
	v_mul_f32_e32 v229, v71, v229
	v_mul_f32_e32 v72, v222, v72
	v_mul_f32_e32 v73, v223, v73
	v_mul_f32_e32 v74, v224, v74
	v_mul_f32_e32 v75, v225, v75
	v_mul_f32_e32 v76, v226, v64
	v_mul_f32_e32 v77, v227, v65
	v_mul_f32_e32 v70, v228, v66
	v_mul_f32_e32 v67, v229, v67
	v_or_b32_e32 v80, 48, v144
	v_mad_i64_i32 v[80:81], s[14:15], v80, s5, v[138:139]
	v_lshl_add_u64 v[68:69], v[80:81], 0, v[112:113]
	v_cvt_pk_bf16_f32 v64, v72, v73
	v_cvt_pk_bf16_f32 v65, v74, v75
	v_cvt_pk_bf16_f32 v66, v76, v77
	v_cvt_pk_bf16_f32 v67, v70, v67
	global_store_dwordx4 v[68:69], v[64:67], off
	s_nop 1
	v_mul_f32_e32 v222, 0xbfb8aa3b, v60
	v_mul_f32_e32 v223, 0xbfb8aa3b, v61
	v_mul_f32_e32 v224, 0xbfb8aa3b, v62
	v_mul_f32_e32 v225, 0xbfb8aa3b, v63
	v_mul_f32_e32 v226, 0xbfb8aa3b, v52
	v_mul_f32_e32 v227, 0xbfb8aa3b, v53
	v_mul_f32_e32 v228, 0xbfb8aa3b, v54
	v_mul_f32_e32 v229, 0xbfb8aa3b, v55
	v_exp_f32_e32 v222, v222
	v_exp_f32_e32 v223, v223
	v_exp_f32_e32 v224, v224
	v_exp_f32_e32 v225, v225
	v_exp_f32_e32 v226, v226
	v_exp_f32_e32 v227, v227
	v_exp_f32_e32 v228, v228
	v_exp_f32_e32 v229, v229
	v_add_f32_e32 v222, 1.0, v222
	v_add_f32_e32 v223, 1.0, v223
	v_add_f32_e32 v224, 1.0, v224
	v_add_f32_e32 v225, 1.0, v225
	v_add_f32_e32 v226, 1.0, v226
	v_add_f32_e32 v227, 1.0, v227
	v_add_f32_e32 v228, 1.0, v228
	v_add_f32_e32 v229, 1.0, v229
	v_rcp_f32_e32 v222, v222
	v_rcp_f32_e32 v223, v223
	v_rcp_f32_e32 v224, v224
	v_rcp_f32_e32 v225, v225
	v_rcp_f32_e32 v226, v226
	v_rcp_f32_e32 v227, v227
	v_rcp_f32_e32 v228, v228
	v_rcp_f32_e32 v229, v229
	v_mul_f32_e32 v222, v60, v222
	v_mul_f32_e32 v223, v61, v223
	v_mul_f32_e32 v224, v62, v224
	v_mul_f32_e32 v225, v63, v225
	v_mul_f32_e32 v226, v52, v226
	v_mul_f32_e32 v227, v53, v227
	v_mul_f32_e32 v228, v54, v228
	v_mul_f32_e32 v229, v55, v229
	v_mul_f32_e32 v56, v222, v56
	v_mul_f32_e32 v57, v223, v57
	v_mul_f32_e32 v58, v224, v58
	v_mul_f32_e32 v59, v225, v59
	v_mul_f32_e32 v60, v226, v48
	v_mul_f32_e32 v61, v227, v49
	v_mul_f32_e32 v54, v228, v50
	v_mul_f32_e32 v51, v229, v51
	v_add_u32_e32 v64, 0x80, v144
	v_mad_i64_i32 v[64:65], s[14:15], v64, s5, v[138:139]
	v_lshl_add_u64 v[52:53], v[64:65], 0, v[112:113]
	v_cvt_pk_bf16_f32 v48, v56, v57
	v_cvt_pk_bf16_f32 v49, v58, v59
	v_cvt_pk_bf16_f32 v50, v60, v61
	v_cvt_pk_bf16_f32 v51, v54, v51
	global_store_dwordx4 v[52:53], v[48:51], off
	s_nop 1
	v_mul_f32_e32 v222, 0xbfb8aa3b, v44
	v_mul_f32_e32 v223, 0xbfb8aa3b, v45
	v_mul_f32_e32 v224, 0xbfb8aa3b, v46
	v_mul_f32_e32 v225, 0xbfb8aa3b, v47
	v_mul_f32_e32 v226, 0xbfb8aa3b, v36
	v_mul_f32_e32 v227, 0xbfb8aa3b, v37
	v_mul_f32_e32 v228, 0xbfb8aa3b, v38
	v_mul_f32_e32 v229, 0xbfb8aa3b, v39
	v_exp_f32_e32 v222, v222
	v_exp_f32_e32 v223, v223
	v_exp_f32_e32 v224, v224
	v_exp_f32_e32 v225, v225
	v_exp_f32_e32 v226, v226
	v_exp_f32_e32 v227, v227
	v_exp_f32_e32 v228, v228
	v_exp_f32_e32 v229, v229
	v_add_f32_e32 v222, 1.0, v222
	v_add_f32_e32 v223, 1.0, v223
	v_add_f32_e32 v224, 1.0, v224
	v_add_f32_e32 v225, 1.0, v225
	v_add_f32_e32 v226, 1.0, v226
	v_add_f32_e32 v227, 1.0, v227
	v_add_f32_e32 v228, 1.0, v228
	v_add_f32_e32 v229, 1.0, v229
	v_rcp_f32_e32 v222, v222
	v_rcp_f32_e32 v223, v223
	v_rcp_f32_e32 v224, v224
	v_rcp_f32_e32 v225, v225
	v_rcp_f32_e32 v226, v226
	v_rcp_f32_e32 v227, v227
	v_rcp_f32_e32 v228, v228
	v_rcp_f32_e32 v229, v229
	v_mul_f32_e32 v222, v44, v222
	v_mul_f32_e32 v223, v45, v223
	v_mul_f32_e32 v224, v46, v224
	v_mul_f32_e32 v225, v47, v225
	v_mul_f32_e32 v226, v36, v226
	v_mul_f32_e32 v227, v37, v227
	v_mul_f32_e32 v228, v38, v228
	v_mul_f32_e32 v229, v39, v229
	v_mul_f32_e32 v40, v222, v40
	v_mul_f32_e32 v41, v223, v41
	v_mul_f32_e32 v42, v224, v42
	v_mul_f32_e32 v43, v225, v43
	v_mul_f32_e32 v44, v226, v32
	v_mul_f32_e32 v45, v227, v33
	v_mul_f32_e32 v38, v228, v34
	v_mul_f32_e32 v35, v229, v35
	v_add_u32_e32 v48, 0x90, v144
	v_mad_i64_i32 v[48:49], s[14:15], v48, s5, v[138:139]
	v_lshl_add_u64 v[36:37], v[48:49], 0, v[112:113]
	v_cvt_pk_bf16_f32 v32, v40, v41
	v_cvt_pk_bf16_f32 v33, v42, v43
	v_cvt_pk_bf16_f32 v34, v44, v45
	v_cvt_pk_bf16_f32 v35, v38, v35
	global_store_dwordx4 v[36:37], v[32:35], off
	s_nop 1
	v_mul_f32_e32 v222, 0xbfb8aa3b, v28
	v_mul_f32_e32 v223, 0xbfb8aa3b, v29
	v_mul_f32_e32 v224, 0xbfb8aa3b, v30
	v_mul_f32_e32 v225, 0xbfb8aa3b, v31
	v_mul_f32_e32 v226, 0xbfb8aa3b, v20
	v_mul_f32_e32 v227, 0xbfb8aa3b, v21
	v_mul_f32_e32 v228, 0xbfb8aa3b, v22
	v_mul_f32_e32 v229, 0xbfb8aa3b, v23
	v_exp_f32_e32 v222, v222
	v_exp_f32_e32 v223, v223
	v_exp_f32_e32 v224, v224
	v_exp_f32_e32 v225, v225
	v_exp_f32_e32 v226, v226
	v_exp_f32_e32 v227, v227
	v_exp_f32_e32 v228, v228
	v_exp_f32_e32 v229, v229
	v_add_f32_e32 v222, 1.0, v222
	v_add_f32_e32 v223, 1.0, v223
	v_add_f32_e32 v224, 1.0, v224
	v_add_f32_e32 v225, 1.0, v225
	v_add_f32_e32 v226, 1.0, v226
	v_add_f32_e32 v227, 1.0, v227
	v_add_f32_e32 v228, 1.0, v228
	v_add_f32_e32 v229, 1.0, v229
	v_rcp_f32_e32 v222, v222
	v_rcp_f32_e32 v223, v223
	v_rcp_f32_e32 v224, v224
	v_rcp_f32_e32 v225, v225
	v_rcp_f32_e32 v226, v226
	v_rcp_f32_e32 v227, v227
	v_rcp_f32_e32 v228, v228
	v_rcp_f32_e32 v229, v229
	v_mul_f32_e32 v222, v28, v222
	v_mul_f32_e32 v223, v29, v223
	v_mul_f32_e32 v224, v30, v224
	v_mul_f32_e32 v225, v31, v225
	v_mul_f32_e32 v226, v20, v226
	v_mul_f32_e32 v227, v21, v227
	v_mul_f32_e32 v228, v22, v228
	v_mul_f32_e32 v229, v23, v229
	v_mul_f32_e32 v24, v222, v24
	v_mul_f32_e32 v25, v223, v25
	v_mul_f32_e32 v26, v224, v26
	v_mul_f32_e32 v27, v225, v27
	v_mul_f32_e32 v28, v226, v16
	v_mul_f32_e32 v29, v227, v17
	v_mul_f32_e32 v22, v228, v18
	v_mul_f32_e32 v19, v229, v19
	v_add_u32_e32 v32, 0xa0, v144
	v_mad_i64_i32 v[32:33], s[14:15], v32, s5, v[138:139]
	v_lshl_add_u64 v[20:21], v[32:33], 0, v[112:113]
	v_cvt_pk_bf16_f32 v16, v24, v25
	v_cvt_pk_bf16_f32 v17, v26, v27
	v_cvt_pk_bf16_f32 v18, v28, v29
	v_cvt_pk_bf16_f32 v19, v22, v19
	global_store_dwordx4 v[20:21], v[16:19], off
	s_nop 1
	v_mul_f32_e32 v222, 0xbfb8aa3b, v12
	v_mul_f32_e32 v223, 0xbfb8aa3b, v13
	v_mul_f32_e32 v224, 0xbfb8aa3b, v14
	v_mul_f32_e32 v225, 0xbfb8aa3b, v15
	v_mul_f32_e32 v226, 0xbfb8aa3b, v4
	v_mul_f32_e32 v227, 0xbfb8aa3b, v5
	v_mul_f32_e32 v228, 0xbfb8aa3b, v6
	v_mul_f32_e32 v229, 0xbfb8aa3b, v7
	v_exp_f32_e32 v222, v222
	v_exp_f32_e32 v223, v223
	v_exp_f32_e32 v224, v224
	v_exp_f32_e32 v225, v225
	v_exp_f32_e32 v226, v226
	v_exp_f32_e32 v227, v227
	v_exp_f32_e32 v228, v228
	v_exp_f32_e32 v229, v229
	v_add_f32_e32 v222, 1.0, v222
	v_add_f32_e32 v223, 1.0, v223
	v_add_f32_e32 v224, 1.0, v224
	v_add_f32_e32 v225, 1.0, v225
	v_add_f32_e32 v226, 1.0, v226
	v_add_f32_e32 v227, 1.0, v227
	v_add_f32_e32 v228, 1.0, v228
	v_add_f32_e32 v229, 1.0, v229
	v_rcp_f32_e32 v222, v222
	v_rcp_f32_e32 v223, v223
	v_rcp_f32_e32 v224, v224
	v_rcp_f32_e32 v225, v225
	v_rcp_f32_e32 v226, v226
	v_rcp_f32_e32 v227, v227
	v_rcp_f32_e32 v228, v228
	v_rcp_f32_e32 v229, v229
	v_mul_f32_e32 v222, v12, v222
	v_mul_f32_e32 v223, v13, v223
	v_mul_f32_e32 v224, v14, v224
	v_mul_f32_e32 v225, v15, v225
	v_mul_f32_e32 v226, v4, v226
	v_mul_f32_e32 v227, v5, v227
	v_mul_f32_e32 v228, v6, v228
	v_mul_f32_e32 v229, v7, v229
	v_mul_f32_e32 v8, v222, v8
	v_mul_f32_e32 v9, v223, v9
	v_mul_f32_e32 v10, v224, v10
	v_mul_f32_e32 v11, v225, v11
	v_mul_f32_e32 v12, v226, v0
	v_mul_f32_e32 v13, v227, v1
	v_mul_f32_e32 v6, v228, v2
	v_mul_f32_e32 v3, v229, v3
	v_add_u32_e32 v16, 0xb0, v144
	v_mad_i64_i32 v[16:17], s[14:15], v16, s5, v[138:139]
	s_mov_b64 s[14:15], s[8:9]
	v_lshl_add_u64 v[4:5], v[16:17], 0, v[112:113]
	v_cvt_pk_bf16_f32 v0, v8, v9
	v_cvt_pk_bf16_f32 v1, v10, v11
	v_cvt_pk_bf16_f32 v2, v12, v13
	v_cvt_pk_bf16_f32 v3, v6, v3
	global_store_dwordx4 v[4:5], v[0:3], off
	s_cbranch_vccz .LBB0_214
	s_waitcnt vmcnt(0)
	v_readlane_b32 s34, v254, 18
	s_cmpk_gt_u32 s21, 0xff
	v_readlane_b32 s35, v254, 19
	v_readlane_b32 s31, v254, 20
	s_cbranch_scc1 .LBB0_221
	s_barrier
